# sec 7.3 store widening: prompt attention unit epilogue uses v_permlane32_swap + 8 dwordx4 stores instead of 16 dwordx2
# speedup vs baseline: 1.0268x; 1.0008x over previous
.LBB0_503:
	s_cmpk_gt_u32 s21, 0xff
	s_waitcnt lgkmcnt(0)
	s_barrier
	s_cbranch_scc1 .LBB0_505
	s_add_u32 s1, s76, s44
	s_addc_u32 s19, s77, s45
	s_lshl_b32 s0, s0, 1
	s_add_u32 s0, s1, s0
	s_addc_u32 s1, s19, 0
	v_lshlrev_b32_e32 v0, 1, v0
	v_lshl_add_u64 v[4:5], s[0:1], 0, v[0:1]
	s_lshl_b32 s0, s20, 14
	v_lshlrev_b32_e32 v0, 1, v202
	s_add_i32 s0, s0, 0
	v_lshl_add_u64 v[80:81], v[4:5], 0, v[0:1]
	v_lshl_add_u32 v0, v203, 4, s0
	ds_read_b128 v[108:111], v0 offset:10240
	ds_read_b128 v[112:115], v0 offset:11264
	ds_read_b128 v[4:7], v0
	ds_read_b128 v[8:11], v0 offset:1024
	ds_read_b128 v[12:15], v0 offset:2048
	ds_read_b128 v[84:87], v0 offset:3072
	s_waitcnt lgkmcnt(4)
	v_pk_mul_f32 v[112:113], v[186:187], v[112:113]
	s_waitcnt lgkmcnt(3)
	v_pk_mul_f32 v[4:5], v[186:187], v[4:5]
	v_pk_fma_f32 v[112:113], v[44:45], v[2:3], v[112:113] op_sel_hi:[1,0,1] neg_lo:[0,0,1] neg_hi:[0,0,1]
	v_pk_mul_f32 v[44:45], v[186:187], v[114:115]
	v_pk_fma_f32 v[82:83], v[64:65], v[2:3], v[4:5] op_sel_hi:[1,0,1] neg_lo:[0,0,1] neg_hi:[0,0,1]
	v_pk_fma_f32 v[114:115], v[46:47], v[2:3], v[44:45] op_sel_hi:[1,0,1] neg_lo:[0,0,1] neg_hi:[0,0,1]
	ds_read_b128 v[44:47], v0 offset:12288
	v_pk_mul_f32 v[6:7], v[186:187], v[6:7]
	v_pk_mul_f32 v[4:5], v[82:83], v[82:83]
	v_pk_fma_f32 v[66:67], v[66:67], v[2:3], v[6:7] op_sel_hi:[1,0,1] neg_lo:[0,0,1] neg_hi:[0,0,1]
	s_waitcnt lgkmcnt(1)
	v_pk_mul_f32 v[64:65], v[186:187], v[84:85]
	s_waitcnt lgkmcnt(0)
	v_pk_mul_f32 v[44:45], v[186:187], v[44:45]
	v_pk_mul_f32 v[84:85], v[186:187], v[86:87]
	v_pk_fma_f32 v[116:117], v[16:17], v[2:3], v[44:45] op_sel_hi:[1,0,1] neg_lo:[0,0,1] neg_hi:[0,0,1]
	v_pk_mul_f32 v[16:17], v[186:187], v[46:47]
	v_pk_mul_f32 v[6:7], v[66:67], v[66:67]
	v_pk_fma_f32 v[118:119], v[18:19], v[2:3], v[16:17] op_sel_hi:[1,0,1] neg_lo:[0,0,1] neg_hi:[0,0,1]
	ds_read_b128 v[16:19], v0 offset:13312
	v_pk_mul_f32 v[8:9], v[186:187], v[8:9]
	v_pk_fma_f32 v[78:79], v[78:79], v[2:3], v[84:85] op_sel_hi:[1,0,1] neg_lo:[0,0,1] neg_hi:[0,0,1]
	ds_read_b128 v[84:87], v0 offset:4096
	ds_read_b128 v[88:91], v0 offset:5120
	s_waitcnt lgkmcnt(2)
	v_pk_mul_f32 v[16:17], v[186:187], v[16:17]
	ds_read_b128 v[92:95], v0 offset:6144
	ds_read_b128 v[96:99], v0 offset:7168
	v_pk_fma_f32 v[120:121], v[20:21], v[2:3], v[16:17] op_sel_hi:[1,0,1] neg_lo:[0,0,1] neg_hi:[0,0,1]
	v_pk_mul_f32 v[16:17], v[186:187], v[18:19]
	ds_read_b128 v[100:103], v0 offset:8192
	ds_read_b128 v[104:107], v0 offset:9216
	v_pk_fma_f32 v[122:123], v[22:23], v[2:3], v[16:17] op_sel_hi:[1,0,1] neg_lo:[0,0,1] neg_hi:[0,0,1]
	ds_read_b128 v[16:19], v0 offset:14336
	v_pk_fma_f32 v[68:69], v[68:69], v[2:3], v[8:9] op_sel_hi:[1,0,1] neg_lo:[0,0,1] neg_hi:[0,0,1]
	v_pk_mul_f32 v[10:11], v[186:187], v[10:11]
	v_pk_mul_f32 v[8:9], v[68:69], v[68:69]
	v_pk_fma_f32 v[70:71], v[70:71], v[2:3], v[10:11] op_sel_hi:[1,0,1] neg_lo:[0,0,1] neg_hi:[0,0,1]
	s_waitcnt lgkmcnt(0)
	v_pk_mul_f32 v[16:17], v[186:187], v[16:17]
	v_pk_mul_f32 v[10:11], v[70:71], v[70:71]
	v_pk_fma_f32 v[124:125], v[24:25], v[2:3], v[16:17] op_sel_hi:[1,0,1] neg_lo:[0,0,1] neg_hi:[0,0,1]
	v_pk_mul_f32 v[16:17], v[186:187], v[18:19]
	v_pk_mul_f32 v[12:13], v[186:187], v[12:13]
	v_pk_fma_f32 v[126:127], v[26:27], v[2:3], v[16:17] op_sel_hi:[1,0,1] neg_lo:[0,0,1] neg_hi:[0,0,1]
	ds_read_b128 v[16:19], v0 offset:15360
	v_add_f32_e32 v0, v4, v5
	v_add_f32_e32 v0, v6, v0
	v_add_f32_e32 v0, v7, v0
	v_add_f32_e32 v0, v8, v0
	v_add_f32_e32 v0, v9, v0
	v_pk_fma_f32 v[72:73], v[72:73], v[2:3], v[12:13] op_sel_hi:[1,0,1] neg_lo:[0,0,1] neg_hi:[0,0,1]
	v_add_f32_e32 v0, v10, v0
	v_pk_mul_f32 v[12:13], v[72:73], v[72:73]
	v_pk_mul_f32 v[14:15], v[186:187], v[14:15]
	v_add_f32_e32 v0, v11, v0
	v_pk_fma_f32 v[74:75], v[74:75], v[2:3], v[14:15] op_sel_hi:[1,0,1] neg_lo:[0,0,1] neg_hi:[0,0,1]
	v_add_f32_e32 v0, v12, v0
	v_pk_mul_f32 v[14:15], v[74:75], v[74:75]
	v_add_f32_e32 v0, v13, v0
	v_pk_fma_f32 v[76:77], v[76:77], v[2:3], v[64:65] op_sel_hi:[1,0,1] neg_lo:[0,0,1] neg_hi:[0,0,1]
	v_add_f32_e32 v0, v14, v0
	v_pk_mul_f32 v[64:65], v[76:77], v[76:77]
	v_add_f32_e32 v0, v15, v0
	v_add_f32_e32 v0, v64, v0
	v_pk_mul_f32 v[132:133], v[78:79], v[78:79]
	v_pk_mul_f32 v[84:85], v[186:187], v[84:85]
	v_add_f32_e32 v0, v65, v0
	v_pk_fma_f32 v[84:85], v[48:49], v[2:3], v[84:85] op_sel_hi:[1,0,1] neg_lo:[0,0,1] neg_hi:[0,0,1]
	v_add_f32_e32 v0, v132, v0
	v_pk_mul_f32 v[48:49], v[84:85], v[84:85]
	v_pk_mul_f32 v[86:87], v[186:187], v[86:87]
	v_add_f32_e32 v0, v133, v0
	v_pk_fma_f32 v[86:87], v[50:51], v[2:3], v[86:87] op_sel_hi:[1,0,1] neg_lo:[0,0,1] neg_hi:[0,0,1]
	v_add_f32_e32 v0, v48, v0
	v_pk_mul_f32 v[50:51], v[86:87], v[86:87]
	v_pk_mul_f32 v[88:89], v[186:187], v[88:89]
	v_add_f32_e32 v0, v49, v0
	v_pk_fma_f32 v[88:89], v[52:53], v[2:3], v[88:89] op_sel_hi:[1,0,1] neg_lo:[0,0,1] neg_hi:[0,0,1]
	v_add_f32_e32 v0, v50, v0
	v_pk_mul_f32 v[52:53], v[88:89], v[88:89]
	v_pk_mul_f32 v[90:91], v[186:187], v[90:91]
	v_add_f32_e32 v0, v51, v0
	v_pk_fma_f32 v[90:91], v[54:55], v[2:3], v[90:91] op_sel_hi:[1,0,1] neg_lo:[0,0,1] neg_hi:[0,0,1]
	v_add_f32_e32 v0, v52, v0
	v_pk_mul_f32 v[54:55], v[90:91], v[90:91]
	v_pk_mul_f32 v[92:93], v[186:187], v[92:93]
	v_add_f32_e32 v0, v53, v0
	v_pk_fma_f32 v[92:93], v[56:57], v[2:3], v[92:93] op_sel_hi:[1,0,1] neg_lo:[0,0,1] neg_hi:[0,0,1]
	v_add_f32_e32 v0, v54, v0
	v_pk_mul_f32 v[56:57], v[92:93], v[92:93]
	v_pk_mul_f32 v[94:95], v[186:187], v[94:95]
	v_add_f32_e32 v0, v55, v0
	v_pk_fma_f32 v[94:95], v[58:59], v[2:3], v[94:95] op_sel_hi:[1,0,1] neg_lo:[0,0,1] neg_hi:[0,0,1]
	v_add_f32_e32 v0, v56, v0
	v_pk_mul_f32 v[58:59], v[94:95], v[94:95]
	v_pk_mul_f32 v[96:97], v[186:187], v[96:97]
	v_add_f32_e32 v0, v57, v0
	v_pk_fma_f32 v[96:97], v[60:61], v[2:3], v[96:97] op_sel_hi:[1,0,1] neg_lo:[0,0,1] neg_hi:[0,0,1]
	v_add_f32_e32 v0, v58, v0
	v_pk_mul_f32 v[60:61], v[96:97], v[96:97]
	v_pk_mul_f32 v[98:99], v[186:187], v[98:99]
	v_add_f32_e32 v0, v59, v0
	v_pk_fma_f32 v[98:99], v[62:63], v[2:3], v[98:99] op_sel_hi:[1,0,1] neg_lo:[0,0,1] neg_hi:[0,0,1]
	v_add_f32_e32 v0, v60, v0
	v_pk_mul_f32 v[62:63], v[98:99], v[98:99]
	v_pk_mul_f32 v[100:101], v[186:187], v[100:101]
	v_add_f32_e32 v0, v61, v0
	v_pk_fma_f32 v[100:101], v[32:33], v[2:3], v[100:101] op_sel_hi:[1,0,1] neg_lo:[0,0,1] neg_hi:[0,0,1]
	v_add_f32_e32 v0, v62, v0
	v_pk_mul_f32 v[32:33], v[100:101], v[100:101]
	v_pk_mul_f32 v[102:103], v[186:187], v[102:103]
	v_add_f32_e32 v0, v63, v0
	v_pk_fma_f32 v[102:103], v[34:35], v[2:3], v[102:103] op_sel_hi:[1,0,1] neg_lo:[0,0,1] neg_hi:[0,0,1]
	v_add_f32_e32 v0, v32, v0
	v_pk_mul_f32 v[34:35], v[102:103], v[102:103]
	v_pk_mul_f32 v[104:105], v[186:187], v[104:105]
	v_add_f32_e32 v0, v33, v0
	v_pk_fma_f32 v[104:105], v[36:37], v[2:3], v[104:105] op_sel_hi:[1,0,1] neg_lo:[0,0,1] neg_hi:[0,0,1]
	v_add_f32_e32 v0, v34, v0
	v_pk_mul_f32 v[36:37], v[104:105], v[104:105]
	v_pk_mul_f32 v[106:107], v[186:187], v[106:107]
	v_add_f32_e32 v0, v35, v0
	v_pk_fma_f32 v[106:107], v[38:39], v[2:3], v[106:107] op_sel_hi:[1,0,1] neg_lo:[0,0,1] neg_hi:[0,0,1]
	v_add_f32_e32 v0, v36, v0
	v_pk_mul_f32 v[38:39], v[106:107], v[106:107]
	v_pk_mul_f32 v[108:109], v[186:187], v[108:109]
	v_add_f32_e32 v0, v37, v0
	v_pk_fma_f32 v[108:109], v[40:41], v[2:3], v[108:109] op_sel_hi:[1,0,1] neg_lo:[0,0,1] neg_hi:[0,0,1]
	v_add_f32_e32 v0, v38, v0
	v_pk_mul_f32 v[40:41], v[108:109], v[108:109]
	v_pk_mul_f32 v[110:111], v[186:187], v[110:111]
	v_add_f32_e32 v0, v39, v0
	v_pk_fma_f32 v[110:111], v[42:43], v[2:3], v[110:111] op_sel_hi:[1,0,1] neg_lo:[0,0,1] neg_hi:[0,0,1]
	v_add_f32_e32 v0, v40, v0
	v_pk_mul_f32 v[42:43], v[110:111], v[110:111]
	v_add_f32_e32 v0, v41, v0
	v_add_f32_e32 v0, v42, v0
	v_pk_mul_f32 v[134:135], v[112:113], v[112:113]
	v_add_f32_e32 v0, v43, v0
	v_add_f32_e32 v0, v134, v0
	v_pk_mul_f32 v[136:137], v[114:115], v[114:115]
	v_add_f32_e32 v0, v135, v0
	v_add_f32_e32 v0, v136, v0
	v_pk_mul_f32 v[44:45], v[116:117], v[116:117]
	v_add_f32_e32 v0, v137, v0
	v_add_f32_e32 v0, v44, v0
	v_pk_mul_f32 v[46:47], v[118:119], v[118:119]
	v_add_f32_e32 v0, v45, v0
	v_add_f32_e32 v0, v46, v0
	v_pk_mul_f32 v[20:21], v[120:121], v[120:121]
	v_add_f32_e32 v0, v47, v0
	v_add_f32_e32 v0, v20, v0
	v_pk_mul_f32 v[22:23], v[122:123], v[122:123]
	v_add_f32_e32 v0, v21, v0
	v_add_f32_e32 v0, v22, v0
	v_pk_mul_f32 v[24:25], v[124:125], v[124:125]
	v_add_f32_e32 v0, v23, v0
	v_add_f32_e32 v0, v24, v0
	v_pk_mul_f32 v[26:27], v[126:127], v[126:127]
	s_waitcnt lgkmcnt(0)
	v_pk_mul_f32 v[16:17], v[186:187], v[16:17]
	v_add_f32_e32 v0, v25, v0
	v_pk_fma_f32 v[128:129], v[28:29], v[2:3], v[16:17] op_sel_hi:[1,0,1] neg_lo:[0,0,1] neg_hi:[0,0,1]
	v_add_f32_e32 v0, v26, v0
	v_pk_mul_f32 v[16:17], v[128:129], v[128:129]
	v_pk_mul_f32 v[18:19], v[186:187], v[18:19]
	v_add_f32_e32 v0, v27, v0
	v_pk_fma_f32 v[130:131], v[30:31], v[2:3], v[18:19] op_sel_hi:[1,0,1] neg_lo:[0,0,1] neg_hi:[0,0,1]
	v_add_f32_e32 v0, v16, v0
	v_pk_mul_f32 v[2:3], v[130:131], v[130:131]
	v_add_f32_e32 v0, v17, v0
	v_add_f32_e32 v0, v2, v0
	v_add_f32_e32 v0, v3, v0
	ds_bpermute_b32 v2, v225, v0
	s_waitcnt lgkmcnt(0)
	v_add_f32_e32 v0, v0, v2
	v_fmamk_f32 v0, v0, 0x3c000000, v207
	v_cmp_gt_f32_e32 vcc, s16, v0
	v_mul_f32_e32 v2, 0x4b800000, v0
	s_nop 0
	v_cndmask_b32_e32 v0, v0, v2, vcc
	v_rsq_f32_e32 v0, v0
	s_nop 0
	v_mul_f32_e32 v2, 0x45800000, v0
	v_cndmask_b32_e32 v0, v0, v2, vcc
	v_lshlrev_b32_e32 v2, 2, v202
	global_load_dwordx4 v[62:65], v2, s[58:59]
	global_load_dwordx4 v[58:61], v2, s[58:59] offset:32
	global_load_dwordx4 v[54:57], v2, s[58:59] offset:64
	global_load_dwordx4 v[50:53], v2, s[58:59] offset:96
	global_load_dwordx4 v[46:49], v2, s[58:59] offset:128
	global_load_dwordx4 v[42:45], v2, s[58:59] offset:160
	global_load_dwordx4 v[38:41], v2, s[58:59] offset:192
	global_load_dwordx4 v[34:37], v2, s[58:59] offset:224
	global_load_dwordx4 v[30:33], v2, s[58:59] offset:256
	global_load_dwordx4 v[26:29], v2, s[58:59] offset:288
	global_load_dwordx4 v[22:25], v2, s[58:59] offset:320
	global_load_dwordx4 v[18:21], v2, s[58:59] offset:352
	global_load_dwordx4 v[14:17], v2, s[58:59] offset:384
	global_load_dwordx4 v[10:13], v2, s[58:59] offset:416
	global_load_dwordx4 v[6:9], v2, s[58:59] offset:448
	s_nop 0
	global_load_dwordx4 v[2:5], v2, s[58:59] offset:480
	v_mul_f32_e32 v0, 0x3f24fd5c, v0
	s_waitcnt vmcnt(15)
	v_pk_mul_f32 v[64:65], v[66:67], v[64:65]
	v_pk_mul_f32 v[62:63], v[82:83], v[62:63]
	s_waitcnt vmcnt(14)
	v_pk_mul_f32 v[58:59], v[68:69], v[58:59]
	v_pk_mul_f32 v[60:61], v[70:71], v[60:61]
	s_waitcnt vmcnt(13)
	v_pk_mul_f32 v[54:55], v[72:73], v[54:55]
	v_pk_mul_f32 v[56:57], v[74:75], v[56:57]
	s_waitcnt vmcnt(12)
	v_pk_mul_f32 v[50:51], v[76:77], v[50:51]
	v_pk_mul_f32 v[52:53], v[78:79], v[52:53]
	s_waitcnt vmcnt(11)
	v_pk_mul_f32 v[48:49], v[86:87], v[48:49]
	v_pk_mul_f32 v[46:47], v[84:85], v[46:47]
	s_waitcnt vmcnt(10)
	v_pk_mul_f32 v[42:43], v[88:89], v[42:43]
	v_pk_mul_f32 v[44:45], v[90:91], v[44:45]
	s_waitcnt vmcnt(9)
	v_pk_mul_f32 v[38:39], v[92:93], v[38:39]
	v_pk_mul_f32 v[40:41], v[94:95], v[40:41]
	s_waitcnt vmcnt(8)
	v_pk_mul_f32 v[34:35], v[96:97], v[34:35]
	v_pk_mul_f32 v[36:37], v[98:99], v[36:37]
	s_waitcnt vmcnt(7)
	v_pk_mul_f32 v[32:33], v[102:103], v[32:33]
	v_pk_mul_f32 v[30:31], v[100:101], v[30:31]
	s_waitcnt vmcnt(6)
	v_pk_mul_f32 v[26:27], v[104:105], v[26:27]
	v_pk_mul_f32 v[28:29], v[106:107], v[28:29]
	s_waitcnt vmcnt(5)
	v_pk_mul_f32 v[22:23], v[108:109], v[22:23]
	v_pk_mul_f32 v[24:25], v[110:111], v[24:25]
	s_waitcnt vmcnt(4)
	v_pk_mul_f32 v[18:19], v[112:113], v[18:19]
	v_pk_mul_f32 v[20:21], v[114:115], v[20:21]
	s_waitcnt vmcnt(3)
	v_pk_mul_f32 v[16:17], v[118:119], v[16:17]
	v_pk_mul_f32 v[14:15], v[116:117], v[14:15]
	s_waitcnt vmcnt(2)
	v_pk_mul_f32 v[10:11], v[120:121], v[10:11]
	v_pk_mul_f32 v[12:13], v[122:123], v[12:13]
	s_waitcnt vmcnt(1)
	v_pk_mul_f32 v[6:7], v[124:125], v[6:7]
	v_pk_mul_f32 v[8:9], v[126:127], v[8:9]
	s_waitcnt vmcnt(0)
	v_pk_mul_f32 v[2:3], v[128:129], v[2:3]
	v_pk_mul_f32 v[4:5], v[130:131], v[4:5]
	v_pk_mul_f32 v[64:65], v[64:65], v[0:1] op_sel_hi:[1,0]
	v_pk_mul_f32 v[62:63], v[62:63], v[0:1] op_sel_hi:[1,0]
	v_pk_mul_f32 v[60:61], v[60:61], v[0:1] op_sel_hi:[1,0]
	v_pk_mul_f32 v[58:59], v[58:59], v[0:1] op_sel_hi:[1,0]
	v_pk_mul_f32 v[56:57], v[56:57], v[0:1] op_sel_hi:[1,0]
	v_pk_mul_f32 v[54:55], v[54:55], v[0:1] op_sel_hi:[1,0]
	v_pk_mul_f32 v[52:53], v[52:53], v[0:1] op_sel_hi:[1,0]
	v_pk_mul_f32 v[50:51], v[50:51], v[0:1] op_sel_hi:[1,0]
	v_pk_mul_f32 v[48:49], v[48:49], v[0:1] op_sel_hi:[1,0]
	v_pk_mul_f32 v[46:47], v[46:47], v[0:1] op_sel_hi:[1,0]
	v_pk_mul_f32 v[44:45], v[44:45], v[0:1] op_sel_hi:[1,0]
	v_pk_mul_f32 v[42:43], v[42:43], v[0:1] op_sel_hi:[1,0]
	v_pk_mul_f32 v[40:41], v[40:41], v[0:1] op_sel_hi:[1,0]
	v_pk_mul_f32 v[38:39], v[38:39], v[0:1] op_sel_hi:[1,0]
	v_pk_mul_f32 v[36:37], v[36:37], v[0:1] op_sel_hi:[1,0]
	v_pk_mul_f32 v[34:35], v[34:35], v[0:1] op_sel_hi:[1,0]
	v_pk_mul_f32 v[32:33], v[32:33], v[0:1] op_sel_hi:[1,0]
	v_pk_mul_f32 v[30:31], v[30:31], v[0:1] op_sel_hi:[1,0]
	v_pk_mul_f32 v[28:29], v[28:29], v[0:1] op_sel_hi:[1,0]
	v_pk_mul_f32 v[26:27], v[26:27], v[0:1] op_sel_hi:[1,0]
	v_pk_mul_f32 v[24:25], v[24:25], v[0:1] op_sel_hi:[1,0]
	v_pk_mul_f32 v[22:23], v[22:23], v[0:1] op_sel_hi:[1,0]
	v_pk_mul_f32 v[20:21], v[20:21], v[0:1] op_sel_hi:[1,0]
	v_pk_mul_f32 v[18:19], v[18:19], v[0:1] op_sel_hi:[1,0]
	v_pk_mul_f32 v[16:17], v[16:17], v[0:1] op_sel_hi:[1,0]
	v_pk_mul_f32 v[14:15], v[14:15], v[0:1] op_sel_hi:[1,0]
	v_pk_mul_f32 v[12:13], v[12:13], v[0:1] op_sel_hi:[1,0]
	v_pk_mul_f32 v[10:11], v[10:11], v[0:1] op_sel_hi:[1,0]
	v_pk_mul_f32 v[8:9], v[8:9], v[0:1] op_sel_hi:[1,0]
	v_pk_mul_f32 v[6:7], v[6:7], v[0:1] op_sel_hi:[1,0]
	v_pk_mul_f32 v[4:5], v[4:5], v[0:1] op_sel_hi:[1,0]
	v_pk_mul_f32 v[2:3], v[2:3], v[0:1] op_sel_hi:[1,0]
	v_cvt_pk_bf16_f32 v61, v60, v61
	v_cvt_pk_bf16_f32 v60, v58, v59
	v_cvt_pk_bf16_f32 v58, v62, v63
	v_cvt_pk_bf16_f32 v59, v64, v65
	v_cvt_pk_bf16_f32 v53, v52, v53
	v_cvt_pk_bf16_f32 v52, v50, v51
	v_cvt_pk_bf16_f32 v50, v54, v55
	v_cvt_pk_bf16_f32 v51, v56, v57
	v_cvt_pk_bf16_f32 v45, v44, v45
	v_cvt_pk_bf16_f32 v44, v42, v43
	v_cvt_pk_bf16_f32 v42, v46, v47
	v_cvt_pk_bf16_f32 v43, v48, v49
	v_cvt_pk_bf16_f32 v37, v36, v37
	v_cvt_pk_bf16_f32 v36, v34, v35
	v_cvt_pk_bf16_f32 v34, v38, v39
	v_cvt_pk_bf16_f32 v35, v40, v41
	v_cvt_pk_bf16_f32 v29, v28, v29
	v_cvt_pk_bf16_f32 v28, v26, v27
	v_cvt_pk_bf16_f32 v26, v30, v31
	v_cvt_pk_bf16_f32 v27, v32, v33
	v_cvt_pk_bf16_f32 v21, v20, v21
	v_cvt_pk_bf16_f32 v20, v18, v19
	v_cvt_pk_bf16_f32 v18, v22, v23
	v_cvt_pk_bf16_f32 v19, v24, v25
	v_cvt_pk_bf16_f32 v13, v12, v13
	v_cvt_pk_bf16_f32 v12, v10, v11
	v_cvt_pk_bf16_f32 v10, v14, v15
	v_cvt_pk_bf16_f32 v11, v16, v17
	v_cvt_pk_bf16_f32 v5, v4, v5
	v_cvt_pk_bf16_f32 v4, v2, v3
	v_cvt_pk_bf16_f32 v2, v6, v7
	v_cvt_pk_bf16_f32 v3, v8, v9
	v_lshlrev_b32_e32 v0, 1, v202
	s_nop 0
	v_lshl_add_u64 v[80:81], v[80:81], 0, v[0:1]
	v_permlane32_swap_b32_e32 v58, v60
	v_permlane32_swap_b32_e32 v59, v61
	v_permlane32_swap_b32_e32 v50, v52
	v_permlane32_swap_b32_e32 v51, v53
	v_permlane32_swap_b32_e32 v42, v44
	v_permlane32_swap_b32_e32 v43, v45
	v_permlane32_swap_b32_e32 v34, v36
	v_permlane32_swap_b32_e32 v35, v37
	v_permlane32_swap_b32_e32 v26, v28
	v_permlane32_swap_b32_e32 v27, v29
	v_permlane32_swap_b32_e32 v18, v20
	v_permlane32_swap_b32_e32 v19, v21
	v_permlane32_swap_b32_e32 v10, v12
	v_permlane32_swap_b32_e32 v11, v13
	v_permlane32_swap_b32_e32 v2, v4
	v_permlane32_swap_b32_e32 v3, v5
	global_store_dwordx4 v[80:81], v[58:61], off
	global_store_dwordx4 v[80:81], v[50:53], off offset:32
	global_store_dwordx4 v[80:81], v[42:45], off offset:64
	global_store_dwordx4 v[80:81], v[34:37], off offset:96
	global_store_dwordx4 v[80:81], v[26:29], off offset:128
	global_store_dwordx4 v[80:81], v[18:21], off offset:160
	global_store_dwordx4 v[80:81], v[10:13], off offset:192
	global_store_dwordx4 v[80:81], v[2:5], off offset:224
